# counted waits in the MLA odd tile: V stores after vmcnt(3) two MFMAs earlier, K stores behind a separate vmcnt(0)
# baseline (speedup 1.0000x reference)
;     ...
;     auto st_tile = [&](int buf) {
;         bf16_t* sK = (bf16_t*)(smem + buf * ATT_BUF); bf16_t* sV = (bf16_t*)(smem + buf * ATT_BUF + 13312); float* sC = (float*)(smem + buf * ATT_BUF + 22528);
; #pragma unroll
;     ...
;                 float mx = fmaxf(s4[0][0].x, s4[1][0].x);
; #pragma unroll
;                 for (int qd = 0; qd < 4; ++qd) {
;                     mx = fmaxf(fmaxf(mx, s4[0][qd].y), s4[1][qd].y);
;                     mx = fmaxf(fmaxf(mx, s4[0][qd].z), s4[1][qd].z);
;                     mx = fmaxf(fmaxf(mx, s4[0][qd].w), s4[1][qd].w);
;                     if (qd < 3) mx = fmaxf(fmaxf(mx, s4[0][qd + 1].x), s4[1][qd + 1].x);
;                 }
;                 mx = xhalf_max(mx);
;                 const float mn = fmaxf(m, mx), alpha = fexp2(m - mn);
;                 m = mn;
;                 f32x4 ps4 = {0.f, 0.f, 0.f, 0.f};
;                 const float nmn = -mn;
;                 const f32x4 nm4 = {nmn, nmn, nmn, nmn};
;                 if (__builtin_amdgcn_ballot_w64(alpha != 1.f) != 0) { o0 *= alpha; o1 *= alpha; }
; #pragma unroll
;                 for (int s2 = 0; s2 < 4; ++s2) {
;                     const int mt = s2 >> 1, s = s2 & 1;
;                     f32x4 da = s4[mt][2 * s] + nm4, db = s4[mt][2 * s + 1] + nm4;
;                     da.x = fexp2(da.x); da.y = fexp2(da.y); da.z = fexp2(da.z); da.w = fexp2(da.w);
;                     db.x = fexp2(db.x); db.y = fexp2(db.y); db.z = fexp2(db.z); db.w = fexp2(db.w);
;                     ps4 += da; ps4 += db;
;                     u32x4 pp;
;                     pp.x = pk2(da.x, da.y); pp.y = pk2(da.z, da.w); pp.z = pk2(db.x, db.y); pp.w = pk2(db.z, db.w);
;                     const bf16x8 pfr = __builtin_bit_cast(bf16x8, pp);
;                     const s16x4 a0 = *(const s16x4*)(sV + r * LS + 16 * s2 + 4 * h), a1 = *(const s16x4*)(sV + r * LS + 16 * s2 + 8 + 4 * h);
;                     const s16x4 b0 = *(const s16x4*)(sV + (32 + r) * LS + 16 * s2 + 4 * h), b1 = *(const s16x4*)(sV + (32 + r) * LS + 16 * s2 + 8 + 4 * h);
;                     const bf16x8 v0 = __builtin_shufflevector(a0, a1, 0, 1, 2, 3, 4, 5, 6, 7), v1 = __builtin_shufflevector(b0, b1, 0, 1, 2, 3, 4, 5, 6, 7);
;                     o0 = MFMA32(v0, pfr, o0);
;                     o1 = MFMA32(v1, pfr, o1);
;                 }
;                 lsum = lsum * alpha + ((ps4.x + ps4.y) + (ps4.z + ps4.w));
.Lm3_back_o:
	s_waitcnt lgkmcnt(4)
	v_mfma_f32_32x32x16_bf16 v[50:65], v[208:211], v[86:89], v[156:171]
	v_exp_f32_e32 v176, v176
	v_exp_f32_e32 v177, v177
	v_exp_f32_e32 v178, v178
	v_mfma_f32_32x32x16_bf16 v[34:49], v[232:235], v[86:89], v[156:171]
	ds_read_b128 v[208:211], v216 offset:96
	ds_read_b128 v[232:235], v216 offset:6752
	v_exp_f32_e32 v179, v179
	v_exp_f32_e32 v180, v180
	v_exp_f32_e32 v181, v181
	s_waitcnt lgkmcnt(4)
	v_mfma_f32_32x32x16_bf16 v[50:65], v[236:239], v[90:93], v[50:65]
	v_exp_f32_e32 v182, v182
	v_exp_f32_e32 v183, v183
	v_cvt_pk_bf16_f32 v142, v176, v177
	v_mfma_f32_32x32x16_bf16 v[34:49], v[240:243], v[90:93], v[34:49]
	ds_read_b128 v[236:239], v231 offset:36096
	ds_read_b128 v[240:243], v231 offset:40704
	v_cvt_pk_bf16_f32 v143, v178, v179
	v_cvt_pk_bf16_f32 v144, v180, v181
	v_cvt_pk_bf16_f32 v145, v182, v183
	v_exp_f32_e32 v184, v184
	s_waitcnt lgkmcnt(4)
	v_mfma_f32_32x32x16_bf16 v[50:65], v[244:247], v[94:97], v[50:65]
	v_exp_f32_e32 v185, v185
	v_exp_f32_e32 v186, v186
	v_exp_f32_e32 v187, v187
	v_mfma_f32_32x32x16_bf16 v[34:49], v[248:251], v[94:97], v[34:49]
	ds_read_b128 v[244:247], v216 offset:128
	ds_read_b128 v[248:251], v216 offset:6784
	v_exp_f32_e32 v188, v188
	v_exp_f32_e32 v189, v189
	v_exp_f32_e32 v190, v190
	s_waitcnt lgkmcnt(4)
	v_mfma_f32_32x32x16_bf16 v[50:65], v[208:211], v[98:101], v[50:65]
	v_exp_f32_e32 v191, v191
	v_cvt_pk_bf16_f32 v146, v184, v185
	v_cvt_pk_bf16_f32 v147, v186, v187
	v_cvt_pk_bf16_f32 v148, v188, v189
	v_mfma_f32_32x32x16_bf16 v[34:49], v[232:235], v[98:101], v[34:49]
	ds_read_b128 v[208:211], v231 offset:36128
	ds_read_b128 v[232:235], v231 offset:40736
	v_cvt_pk_bf16_f32 v149, v190, v191
	v_exp_f32_e32 v192, v192
	v_exp_f32_e32 v193, v193
	s_waitcnt lgkmcnt(4)
	v_mfma_f32_32x32x16_bf16 v[18:33], v[236:239], v[142:145], v[18:33]
	v_exp_f32_e32 v194, v194
	v_exp_f32_e32 v195, v195
	v_exp_f32_e32 v196, v196
	v_mfma_f32_32x32x16_bf16 v[2:17], v[240:243], v[142:145], v[2:17]
	s_waitcnt vmcnt(3)
	ds_write2_b64 v130, v[78:79], v[80:81] offset1:2
	ds_read_b128 v[236:239], v216 offset:160
	ds_read_b128 v[240:243], v216 offset:6816
	v_exp_f32_e32 v197, v197
	v_exp_f32_e32 v198, v198
	v_exp_f32_e32 v199, v199
	s_waitcnt lgkmcnt(5)
	v_mfma_f32_32x32x16_bf16 v[50:65], v[244:247], v[102:105], v[50:65]
	ds_write2_b64 v132, v[82:83], v[84:85] offset1:2
	v_cvt_pk_bf16_f32 v150, v192, v193
	v_cvt_pk_bf16_f32 v151, v194, v195
	v_cvt_pk_bf16_f32 v152, v196, v197
	v_cvt_pk_bf16_f32 v153, v198, v199
	v_exp_f32_e32 v200, v200
	v_mfma_f32_32x32x16_bf16 v[34:49], v[248:251], v[102:105], v[34:49]
	ds_read_b128 v[244:247], v231 offset:36160
	ds_read_b128 v[248:251], v231 offset:40768
	v_exp_f32_e32 v201, v201
	v_exp_f32_e32 v202, v202
	v_exp_f32_e32 v203, v203
	s_waitcnt lgkmcnt(6)
	v_mfma_f32_32x32x16_bf16 v[18:33], v[208:211], v[146:149], v[18:33]
	v_exp_f32_e32 v204, v204
	v_exp_f32_e32 v205, v205
	v_mfma_f32_32x32x16_bf16 v[2:17], v[232:235], v[146:149], v[2:17]
	s_waitcnt vmcnt(0)
	ds_write_b128 v127, v[66:69] offset:22784
	ds_read_b128 v[208:211], v231 offset:36192
	ds_read_b128 v[232:235], v231 offset:40800
	v_exp_f32_e32 v206, v206
	v_exp_f32_e32 v207, v207
	v_cvt_pk_bf16_f32 v142, v200, v201
	v_cvt_pk_bf16_f32 v143, v202, v203
	s_waitcnt lgkmcnt(6)
	v_mfma_f32_32x32x16_bf16 v[50:65], v[236:239], v[106:109], v[50:65]
	ds_write_b128 v128, v[70:73] offset:22784
	v_cvt_pk_bf16_f32 v144, v204, v205
	v_cvt_pk_bf16_f32 v145, v206, v207
	v_add_f32_e32 v141, v176, v177
	v_add_f32_e32 v154, v178, v179
	v_add_f32_e32 v212, v180, v181
	v_add_f32_e32 v213, v182, v183
	v_mfma_f32_32x32x16_bf16 v[34:49], v[240:243], v[106:109], v[34:49]
	ds_write_b128 v129, v[74:77] offset:22784
	v_add_f32_e32 v141, v141, v154
	v_add_f32_e32 v212, v212, v213
	v_add_f32_e32 v230, v141, v212
	v_add_f32_e32 v141, v184, v185
	v_add_f32_e32 v154, v186, v187
	v_add_f32_e32 v212, v188, v189
	s_waitcnt lgkmcnt(5)
	v_mfma_f32_32x32x16_bf16 v[18:33], v[244:247], v[150:153], v[18:33]
	v_add_f32_e32 v213, v190, v191
	v_add_f32_e32 v141, v141, v154
	v_add_f32_e32 v212, v212, v213
	v_add_f32_e32 v141, v141, v212
	v_add_f32_e32 v230, v230, v141
	v_mfma_f32_32x32x16_bf16 v[2:17], v[248:251], v[150:153], v[2:17]
	v_add_f32_e32 v141, v192, v193
	v_add_f32_e32 v154, v194, v195
	v_add_f32_e32 v212, v196, v197
	v_add_f32_e32 v213, v198, v199
	v_add_f32_e32 v141, v141, v154
	v_add_f32_e32 v212, v212, v213
	s_waitcnt lgkmcnt(2)
	v_mfma_f32_32x32x16_bf16 v[18:33], v[208:211], v[142:145], v[18:33]
	v_add_f32_e32 v141, v141, v212
	v_add_f32_e32 v230, v230, v141
	v_add_f32_e32 v141, v200, v201
	v_add_f32_e32 v154, v202, v203
	v_add_f32_e32 v212, v204, v205
	v_mfma_f32_32x32x16_bf16 v[2:17], v[232:235], v[142:145], v[2:17]
	v_add_f32_e32 v213, v206, v207
	v_add_f32_e32 v141, v141, v154
	v_add_f32_e32 v212, v212, v213
	v_add_f32_e32 v141, v141, v212
	v_add_f32_e32 v230, v230, v141
	v_add_f32_e32 v135, v135, v230
	s_add_i32 s12, s12, 1
	s_add_i32 s16, s16, 64
	s_branch .Lm3_even
